# rflate: out-proj epilogue consumes the last residual step just before its own store step (counted vmcnt(29)) instead of first; on top of v85
# speedup vs baseline: 1.0042x; 1.0042x over previous
; #define GAS __attribute__((address_space(1)))
; __device__ __forceinline__ unsigned cvt_pk_bf16(float lo, float hi) { unsigned r; asm volatile("v_cvt_pk_bf16_f32 %0, %1, %2" : "=v"(r) : "v"(lo), "v"(hi)); return r; }
; __device__ __forceinline__ float bf_lo(unsigned w) { return __uint_as_float(w << 16); }
; __device__ __forceinline__ float bf_hi(unsigned w) { return __uint_as_float(w & 0xffff0000u); }
;     __device__ __forceinline__ void operator()(const f32x4 (&acc)[2][2][4][2], const Unit& u, int wr, int wc, int fr, int fq, const PG8_LAS float* tab) const {
; #pragma unroll
;         for (int ai = 0; ai < 2; ++ai)
; #pragma unroll
;             for (int m = 0; m < 4; ++m) {
;                 const int row = u.pm * BM + ai * HALF + wr * 64 + m * 16 + fr;
;                 const float ra = tab[ai * HALF + wr * 64 + m * 16 + fr];
;                 const GAS float* xo = (const GAS float*)(row < 16384 ? x0a + (size_t)row * 2048 : x0b + (size_t)(row - 16384) * 2048);
;                 GAS bf16_t* xr = (GAS bf16_t*)XN + (size_t)row * 2048;
;                 float ssq = 0.f;
; #pragma unroll
;                 for (int bj = 0; bj < 2; ++bj) {
;                     const int col0 = u.pn * BM + bj * HALF + wc * 32 + 8 * fq;
;                     f32x4 a0, a1;
;                     if (mode == 0) { a0 = *(const GAS f32x4*)(xo + col0); a1 = *(const GAS f32x4*)(xo + col0 + 4); }
;                     else { const u32x4 w = *(const GAS u32x4*)(xr + col0);
;                         a0 = (f32x4){bf_lo(w.x), bf_hi(w.x), bf_lo(w.y), bf_hi(w.y)}; a1 = (f32x4){bf_lo(w.z), bf_hi(w.z), bf_lo(w.w), bf_hi(w.w)}; }
;                     const f32x4 v0 = a0 + acc[ai][bj][m][0] * ra, v1 = a1 + acc[ai][bj][m][1] * ra;
;                     ssq += (v0[0] * v0[0] + v0[1] * v0[1]) + (v0[2] * v0[2] + v0[3] * v0[3]) + (v1[0] * v1[0] + v1[1] * v1[1]) + (v1[2] * v1[2] + v1[3] * v1[3]);
;                     u32x4 w; w.x = cvt_pk_bf16(v0[0], v0[1]); w.y = cvt_pk_bf16(v0[2], v0[3]); w.z = cvt_pk_bf16(v1[0], v1[1]); w.w = cvt_pk_bf16(v1[2], v1[3]);
;                     *(GAS u32x4*)(xr + col0) = w;
;                 }
;                 { const int ln = fr + 16 * fq; ssq += shx(ssq, ln, 16); ssq = x32_sum(ssq); }
;                 if (fq == 0) unsafeAtomicAdd(SSn + row, ssq);
.LBB0_611:
	s_lshl_b32 s6, s3, 20
	s_lshl_b32 s7, s0, 9
	s_add_u32 s6, s6, s7
	s_add_u32 s24, s58, s6
	s_addc_u32 s25, s59, 0
	v_lshlrev_b32_e32 v146, 12, v1
	v_lshl_add_u32 v146, v173, 1, v146
	s_lshl_b32 s6, s3, 10
	s_add_u32 s26, s12, s6
	s_addc_u32 s27, s13, 0
	ds_read_b32 v130, v252 offset:0
	ds_read_b32 v132, v252 offset:64
	ds_read_b32 v134, v252 offset:128
	ds_read_b32 v136, v252 offset:192
	ds_read_b32 v131, v252 offset:512
	ds_read_b32 v133, v252 offset:576
	ds_read_b32 v135, v252 offset:640
	ds_read_b32 v137, v252 offset:704
	s_waitcnt lgkmcnt(0)
	v_pk_mul_f32 v[126:127], v[126:127], v[130:131] op_sel_hi:[1,0]
	v_pk_mul_f32 v[128:129], v[128:129], v[130:131] op_sel_hi:[1,0]
	v_pk_mul_f32 v[122:123], v[122:123], v[130:131] op_sel_hi:[1,0]
	v_pk_mul_f32 v[124:125], v[124:125], v[130:131] op_sel_hi:[1,0]
	v_cvt_pk_bf16_f32 v158, v126, v127
	v_cvt_pk_bf16_f32 v159, v128, v129
	v_cvt_pk_bf16_f32 v160, v122, v123
	v_cvt_pk_bf16_f32 v161, v124, v125
	s_mov_b64 s[72:73], s[24:25]
	global_store_dwordx4 v146, v[158:161], s[72:73] offset:0
	v_mul_f32_e32 v175, v127, v127
	v_mul_f32_e32 v253, v129, v129
	v_fmac_f32_e32 v175, v126, v126
	v_fmac_f32_e32 v253, v128, v128
	v_add_f32_e32 v147, v175, v253
	v_mul_f32_e32 v253, v123, v123
	v_fmac_f32_e32 v253, v122, v122
	v_mul_f32_e32 v175, v125, v125
	v_add_f32_e32 v147, v253, v147
	v_fmac_f32_e32 v175, v124, v124
	v_add_f32_e32 v147, v175, v147
	v_pk_mul_f32 v[118:119], v[118:119], v[130:131] op_sel_hi:[1,0]
	v_pk_mul_f32 v[120:121], v[120:121], v[130:131] op_sel_hi:[1,0]
	v_pk_mul_f32 v[114:115], v[114:115], v[130:131] op_sel_hi:[1,0]
	v_pk_mul_f32 v[116:117], v[116:117], v[130:131] op_sel_hi:[1,0]
	v_cvt_pk_bf16_f32 v162, v118, v119
	v_cvt_pk_bf16_f32 v163, v120, v121
	v_cvt_pk_bf16_f32 v164, v114, v115
	v_cvt_pk_bf16_f32 v165, v116, v117
	global_store_dwordx4 v146, v[162:165], s[72:73] offset:256
	v_mul_f32_e32 v175, v119, v119
	v_mul_f32_e32 v253, v121, v121
	v_fmac_f32_e32 v175, v118, v118
	v_fmac_f32_e32 v253, v120, v120
	v_add_f32_e32 v166, v175, v253
	v_mul_f32_e32 v253, v115, v115
	v_fmac_f32_e32 v253, v114, v114
	v_mul_f32_e32 v175, v117, v117
	v_add_f32_e32 v166, v253, v166
	v_fmac_f32_e32 v175, v116, v116
	v_add_f32_e32 v166, v175, v166
	v_add_f32_e32 v166, v147, v166
	ds_bpermute_b32 v167, v172, v166
	v_pk_mul_f32 v[110:111], v[110:111], v[132:133] op_sel_hi:[1,0]
	v_pk_mul_f32 v[112:113], v[112:113], v[132:133] op_sel_hi:[1,0]
	v_pk_mul_f32 v[106:107], v[106:107], v[132:133] op_sel_hi:[1,0]
	v_pk_mul_f32 v[108:109], v[108:109], v[132:133] op_sel_hi:[1,0]
	v_cvt_pk_bf16_f32 v158, v110, v111
	v_cvt_pk_bf16_f32 v159, v112, v113
	v_cvt_pk_bf16_f32 v160, v106, v107
	v_cvt_pk_bf16_f32 v161, v108, v109
	s_add_u32 s72, s24, 0x10000
	s_addc_u32 s73, s25, 0
	global_store_dwordx4 v146, v[158:161], s[72:73] offset:0
	v_mul_f32_e32 v175, v111, v111
	v_mul_f32_e32 v253, v113, v113
	v_fmac_f32_e32 v175, v110, v110
	v_fmac_f32_e32 v253, v112, v112
	v_add_f32_e32 v147, v175, v253
	v_mul_f32_e32 v253, v107, v107
	v_fmac_f32_e32 v253, v106, v106
	v_mul_f32_e32 v175, v109, v109
	v_add_f32_e32 v147, v253, v147
	v_fmac_f32_e32 v175, v108, v108
	v_add_f32_e32 v147, v175, v147
	v_pk_mul_f32 v[102:103], v[102:103], v[132:133] op_sel_hi:[1,0]
	v_pk_mul_f32 v[104:105], v[104:105], v[132:133] op_sel_hi:[1,0]
	v_pk_mul_f32 v[98:99], v[98:99], v[132:133] op_sel_hi:[1,0]
	v_pk_mul_f32 v[100:101], v[100:101], v[132:133] op_sel_hi:[1,0]
	v_cvt_pk_bf16_f32 v162, v102, v103
	v_cvt_pk_bf16_f32 v163, v104, v105
	v_cvt_pk_bf16_f32 v164, v98, v99
	v_cvt_pk_bf16_f32 v165, v100, v101
	global_store_dwordx4 v146, v[162:165], s[72:73] offset:256
	v_mul_f32_e32 v175, v103, v103
	v_mul_f32_e32 v253, v105, v105
	v_fmac_f32_e32 v175, v102, v102
	v_fmac_f32_e32 v253, v104, v104
	v_add_f32_e32 v168, v175, v253
	v_mul_f32_e32 v253, v99, v99
	v_fmac_f32_e32 v253, v98, v98
	v_mul_f32_e32 v175, v101, v101
	v_add_f32_e32 v168, v253, v168
	v_fmac_f32_e32 v175, v100, v100
	v_add_f32_e32 v168, v175, v168
	v_add_f32_e32 v168, v147, v168
	s_waitcnt lgkmcnt(0)
	v_add_f32_e32 v166, v166, v167
	v_mov_b32_e32 v167, v166
	s_nop 1
	v_permlane32_swap_b32_e32 v166, v167
	s_and_saveexec_b64 s[6:7], s[8:9]
	v_add_f32_e32 v166, v166, v167
	v_lshlrev_b32_e32 v167, 2, v1
	global_atomic_add_f32 v167, v166, s[26:27] offset:0
	s_mov_b64 exec, s[6:7]
	ds_bpermute_b32 v169, v172, v168
	v_pk_mul_f32 v[94:95], v[94:95], v[134:135] op_sel_hi:[1,0]
	v_pk_mul_f32 v[96:97], v[96:97], v[134:135] op_sel_hi:[1,0]
	v_pk_mul_f32 v[90:91], v[90:91], v[134:135] op_sel_hi:[1,0]
	v_pk_mul_f32 v[92:93], v[92:93], v[134:135] op_sel_hi:[1,0]
	v_cvt_pk_bf16_f32 v158, v94, v95
	v_cvt_pk_bf16_f32 v159, v96, v97
	v_cvt_pk_bf16_f32 v160, v90, v91
	v_cvt_pk_bf16_f32 v161, v92, v93
	s_add_u32 s72, s24, 0x20000
	s_addc_u32 s73, s25, 0
	global_store_dwordx4 v146, v[158:161], s[72:73] offset:0
	v_mul_f32_e32 v175, v95, v95
	v_mul_f32_e32 v253, v97, v97
	v_fmac_f32_e32 v175, v94, v94
	v_fmac_f32_e32 v253, v96, v96
	v_add_f32_e32 v147, v175, v253
	v_mul_f32_e32 v253, v91, v91
	v_fmac_f32_e32 v253, v90, v90
	v_mul_f32_e32 v175, v93, v93
	v_add_f32_e32 v147, v253, v147
	v_fmac_f32_e32 v175, v92, v92
	v_add_f32_e32 v147, v175, v147
	v_pk_mul_f32 v[86:87], v[86:87], v[134:135] op_sel_hi:[1,0]
	v_pk_mul_f32 v[88:89], v[88:89], v[134:135] op_sel_hi:[1,0]
	v_pk_mul_f32 v[82:83], v[82:83], v[134:135] op_sel_hi:[1,0]
	v_pk_mul_f32 v[84:85], v[84:85], v[134:135] op_sel_hi:[1,0]
	v_cvt_pk_bf16_f32 v162, v86, v87
	v_cvt_pk_bf16_f32 v163, v88, v89
	v_cvt_pk_bf16_f32 v164, v82, v83
	v_cvt_pk_bf16_f32 v165, v84, v85
	global_store_dwordx4 v146, v[162:165], s[72:73] offset:256
	v_mul_f32_e32 v175, v87, v87
	v_mul_f32_e32 v253, v89, v89
	v_fmac_f32_e32 v175, v86, v86
	v_fmac_f32_e32 v253, v88, v88
	v_add_f32_e32 v166, v175, v253
	v_mul_f32_e32 v253, v83, v83
	v_fmac_f32_e32 v253, v82, v82
	v_mul_f32_e32 v175, v85, v85
	v_add_f32_e32 v166, v253, v166
	v_fmac_f32_e32 v175, v84, v84
	v_add_f32_e32 v166, v175, v166
	v_add_f32_e32 v166, v147, v166
	s_waitcnt lgkmcnt(0)
; #define GAS __attribute__((address_space(1)))
; __device__ __forceinline__ unsigned cvt_pk_bf16(float lo, float hi) { unsigned r; asm volatile("v_cvt_pk_bf16_f32 %0, %1, %2" : "=v"(r) : "v"(lo), "v"(hi)); return r; }
; __device__ __forceinline__ float bf_lo(unsigned w) { return __uint_as_float(w << 16); }
; __device__ __forceinline__ float bf_hi(unsigned w) { return __uint_as_float(w & 0xffff0000u); }
;     __device__ __forceinline__ void operator()(const f32x4 (&acc)[2][2][4][2], const Unit& u, int wr, int wc, int fr, int fq, const PG8_LAS float* tab) const {
; #pragma unroll
;         for (int ai = 0; ai < 2; ++ai)
; #pragma unroll
;             for (int m = 0; m < 4; ++m) {
;                 const int row = u.pm * BM + ai * HALF + wr * 64 + m * 16 + fr;
;                 const float ra = tab[ai * HALF + wr * 64 + m * 16 + fr];
;                 const GAS float* xo = (const GAS float*)(row < 16384 ? x0a + (size_t)row * 2048 : x0b + (size_t)(row - 16384) * 2048);
;                 GAS bf16_t* xr = (GAS bf16_t*)XN + (size_t)row * 2048;
;                 float ssq = 0.f;
; #pragma unroll
;                 for (int bj = 0; bj < 2; ++bj) {
;                     const int col0 = u.pn * BM + bj * HALF + wc * 32 + 8 * fq;
;                     f32x4 a0, a1;
;                     if (mode == 0) { a0 = *(const GAS f32x4*)(xo + col0); a1 = *(const GAS f32x4*)(xo + col0 + 4); }
;                     else { const u32x4 w = *(const GAS u32x4*)(xr + col0);
;                         a0 = (f32x4){bf_lo(w.x), bf_hi(w.x), bf_lo(w.y), bf_hi(w.y)}; a1 = (f32x4){bf_lo(w.z), bf_hi(w.z), bf_lo(w.w), bf_hi(w.w)}; }
;                     const f32x4 v0 = a0 + acc[ai][bj][m][0] * ra, v1 = a1 + acc[ai][bj][m][1] * ra;
;                     ssq += (v0[0] * v0[0] + v0[1] * v0[1]) + (v0[2] * v0[2] + v0[3] * v0[3]) + (v1[0] * v1[0] + v1[1] * v1[1]) + (v1[2] * v1[2] + v1[3] * v1[3]);
;                     u32x4 w; w.x = cvt_pk_bf16(v0[0], v0[1]); w.y = cvt_pk_bf16(v0[2], v0[3]); w.z = cvt_pk_bf16(v1[0], v1[1]); w.w = cvt_pk_bf16(v1[2], v1[3]);
;                     *(GAS u32x4*)(xr + col0) = w;
;                 }
;                 { const int ln = fr + 16 * fq; ssq += shx(ssq, ln, 16); ssq = x32_sum(ssq); }
;                 if (fq == 0) unsafeAtomicAdd(SSn + row, ssq);
	v_add_f32_e32 v168, v168, v169
	v_mov_b32_e32 v169, v168
	s_nop 1
	v_permlane32_swap_b32_e32 v168, v169
	s_and_saveexec_b64 s[6:7], s[8:9]
	v_add_f32_e32 v168, v168, v169
	v_lshlrev_b32_e32 v169, 2, v1
	global_atomic_add_f32 v169, v168, s[26:27] offset:64
	s_mov_b64 exec, s[6:7]
	ds_bpermute_b32 v167, v172, v166
	v_pk_mul_f32 v[78:79], v[78:79], v[136:137] op_sel_hi:[1,0]
	v_pk_mul_f32 v[80:81], v[80:81], v[136:137] op_sel_hi:[1,0]
	v_pk_mul_f32 v[74:75], v[74:75], v[136:137] op_sel_hi:[1,0]
	v_pk_mul_f32 v[76:77], v[76:77], v[136:137] op_sel_hi:[1,0]
	v_cvt_pk_bf16_f32 v158, v78, v79
	v_cvt_pk_bf16_f32 v159, v80, v81
	v_cvt_pk_bf16_f32 v160, v74, v75
	v_cvt_pk_bf16_f32 v161, v76, v77
	s_add_u32 s72, s24, 0x30000
	s_addc_u32 s73, s25, 0
	global_store_dwordx4 v146, v[158:161], s[72:73] offset:0
	v_mul_f32_e32 v175, v79, v79
	v_mul_f32_e32 v253, v81, v81
	v_fmac_f32_e32 v175, v78, v78
	v_fmac_f32_e32 v253, v80, v80
	v_add_f32_e32 v147, v175, v253
	v_mul_f32_e32 v253, v75, v75
	v_fmac_f32_e32 v253, v74, v74
	v_mul_f32_e32 v175, v77, v77
	v_add_f32_e32 v147, v253, v147
	v_fmac_f32_e32 v175, v76, v76
	v_add_f32_e32 v147, v175, v147
	v_pk_mul_f32 v[70:71], v[70:71], v[136:137] op_sel_hi:[1,0]
	v_pk_mul_f32 v[72:73], v[72:73], v[136:137] op_sel_hi:[1,0]
	v_pk_mul_f32 v[66:67], v[66:67], v[136:137] op_sel_hi:[1,0]
	v_pk_mul_f32 v[68:69], v[68:69], v[136:137] op_sel_hi:[1,0]
	v_cvt_pk_bf16_f32 v162, v70, v71
	v_cvt_pk_bf16_f32 v163, v72, v73
	v_cvt_pk_bf16_f32 v164, v66, v67
	v_cvt_pk_bf16_f32 v165, v68, v69
	global_store_dwordx4 v146, v[162:165], s[72:73] offset:256
	v_mul_f32_e32 v175, v71, v71
	v_mul_f32_e32 v253, v73, v73
	v_fmac_f32_e32 v175, v70, v70
	v_fmac_f32_e32 v253, v72, v72
	v_add_f32_e32 v168, v175, v253
	v_mul_f32_e32 v253, v67, v67
	v_fmac_f32_e32 v253, v66, v66
	v_mul_f32_e32 v175, v69, v69
	v_add_f32_e32 v168, v253, v168
	v_fmac_f32_e32 v175, v68, v68
	v_add_f32_e32 v168, v175, v168
	v_add_f32_e32 v168, v147, v168
	s_waitcnt lgkmcnt(0)
	v_add_f32_e32 v166, v166, v167
	v_mov_b32_e32 v167, v166
	s_nop 1
	v_permlane32_swap_b32_e32 v166, v167
	s_and_saveexec_b64 s[6:7], s[8:9]
	v_add_f32_e32 v166, v166, v167
	v_lshlrev_b32_e32 v167, 2, v1
	global_atomic_add_f32 v167, v166, s[26:27] offset:128
	s_mov_b64 exec, s[6:7]
	ds_bpermute_b32 v169, v172, v168
	v_mov_b32_e32 v130, v131
	v_mov_b32_e32 v132, v133
	v_mov_b32_e32 v134, v135
	v_mov_b32_e32 v136, v137
	v_pk_mul_f32 v[62:63], v[62:63], v[130:131] op_sel_hi:[1,0]
	v_pk_mul_f32 v[64:65], v[64:65], v[130:131] op_sel_hi:[1,0]
	v_pk_mul_f32 v[58:59], v[58:59], v[130:131] op_sel_hi:[1,0]
	v_pk_mul_f32 v[60:61], v[60:61], v[130:131] op_sel_hi:[1,0]
	v_cvt_pk_bf16_f32 v158, v62, v63
	v_cvt_pk_bf16_f32 v159, v64, v65
	v_cvt_pk_bf16_f32 v160, v58, v59
	v_cvt_pk_bf16_f32 v161, v60, v61
	s_add_u32 s72, s24, 0x80000
	s_addc_u32 s73, s25, 0
	global_store_dwordx4 v146, v[158:161], s[72:73] offset:0
	v_mul_f32_e32 v175, v63, v63
	v_mul_f32_e32 v253, v65, v65
	v_fmac_f32_e32 v175, v62, v62
	v_fmac_f32_e32 v253, v64, v64
	v_add_f32_e32 v147, v175, v253
	v_mul_f32_e32 v253, v59, v59
	v_fmac_f32_e32 v253, v58, v58
	v_mul_f32_e32 v175, v61, v61
	v_add_f32_e32 v147, v253, v147
	v_fmac_f32_e32 v175, v60, v60
	v_add_f32_e32 v147, v175, v147
	v_pk_mul_f32 v[54:55], v[54:55], v[130:131] op_sel_hi:[1,0]
	v_pk_mul_f32 v[56:57], v[56:57], v[130:131] op_sel_hi:[1,0]
	v_pk_mul_f32 v[50:51], v[50:51], v[130:131] op_sel_hi:[1,0]
	v_pk_mul_f32 v[52:53], v[52:53], v[130:131] op_sel_hi:[1,0]
	v_cvt_pk_bf16_f32 v162, v54, v55
	v_cvt_pk_bf16_f32 v163, v56, v57
	v_cvt_pk_bf16_f32 v164, v50, v51
	v_cvt_pk_bf16_f32 v165, v52, v53
	global_store_dwordx4 v146, v[162:165], s[72:73] offset:256
	v_mul_f32_e32 v175, v55, v55
	v_mul_f32_e32 v253, v57, v57
	v_fmac_f32_e32 v175, v54, v54
	v_fmac_f32_e32 v253, v56, v56
	v_add_f32_e32 v166, v175, v253
	v_mul_f32_e32 v253, v51, v51
	v_fmac_f32_e32 v253, v50, v50
	v_mul_f32_e32 v175, v53, v53
	v_add_f32_e32 v166, v253, v166
	v_fmac_f32_e32 v175, v52, v52
	v_add_f32_e32 v166, v175, v166
	v_add_f32_e32 v166, v147, v166
	s_waitcnt lgkmcnt(0)
	v_add_f32_e32 v168, v168, v169
	v_mov_b32_e32 v169, v168
	s_nop 1
	v_permlane32_swap_b32_e32 v168, v169
	s_and_saveexec_b64 s[6:7], s[8:9]
	v_add_f32_e32 v168, v168, v169
	v_lshlrev_b32_e32 v169, 2, v1
	global_atomic_add_f32 v169, v168, s[26:27] offset:192
	s_mov_b64 exec, s[6:7]
	ds_bpermute_b32 v167, v172, v166
	v_pk_mul_f32 v[46:47], v[46:47], v[132:133] op_sel_hi:[1,0]
	v_pk_mul_f32 v[48:49], v[48:49], v[132:133] op_sel_hi:[1,0]
	v_pk_mul_f32 v[42:43], v[42:43], v[132:133] op_sel_hi:[1,0]
	v_pk_mul_f32 v[44:45], v[44:45], v[132:133] op_sel_hi:[1,0]
	v_cvt_pk_bf16_f32 v158, v46, v47
	v_cvt_pk_bf16_f32 v159, v48, v49
	v_cvt_pk_bf16_f32 v160, v42, v43
	v_cvt_pk_bf16_f32 v161, v44, v45
	s_add_u32 s72, s24, 0x90000
	s_addc_u32 s73, s25, 0
	global_store_dwordx4 v146, v[158:161], s[72:73] offset:0
	v_mul_f32_e32 v175, v47, v47
	v_mul_f32_e32 v253, v49, v49
	v_fmac_f32_e32 v175, v46, v46
	v_fmac_f32_e32 v253, v48, v48
	v_add_f32_e32 v147, v175, v253
	v_mul_f32_e32 v253, v43, v43
	v_fmac_f32_e32 v253, v42, v42
	v_mul_f32_e32 v175, v45, v45
	v_add_f32_e32 v147, v253, v147
	v_fmac_f32_e32 v175, v44, v44
	v_add_f32_e32 v147, v175, v147
	v_pk_mul_f32 v[38:39], v[38:39], v[132:133] op_sel_hi:[1,0]
	v_pk_mul_f32 v[40:41], v[40:41], v[132:133] op_sel_hi:[1,0]
	v_pk_mul_f32 v[34:35], v[34:35], v[132:133] op_sel_hi:[1,0]
	v_pk_mul_f32 v[36:37], v[36:37], v[132:133] op_sel_hi:[1,0]
	v_cvt_pk_bf16_f32 v162, v38, v39
	v_cvt_pk_bf16_f32 v163, v40, v41
	v_cvt_pk_bf16_f32 v164, v34, v35
	v_cvt_pk_bf16_f32 v165, v36, v37
	global_store_dwordx4 v146, v[162:165], s[72:73] offset:256
	v_mul_f32_e32 v175, v39, v39
	v_mul_f32_e32 v253, v41, v41
	v_fmac_f32_e32 v175, v38, v38
	v_fmac_f32_e32 v253, v40, v40
	v_add_f32_e32 v168, v175, v253
	v_mul_f32_e32 v253, v35, v35
	v_fmac_f32_e32 v253, v34, v34
	v_mul_f32_e32 v175, v37, v37
	v_add_f32_e32 v168, v253, v168
	v_fmac_f32_e32 v175, v36, v36
	v_add_f32_e32 v168, v175, v168
	v_add_f32_e32 v168, v147, v168
	s_waitcnt lgkmcnt(0)
; #define GAS __attribute__((address_space(1)))
; __device__ __forceinline__ unsigned cvt_pk_bf16(float lo, float hi) { unsigned r; asm volatile("v_cvt_pk_bf16_f32 %0, %1, %2" : "=v"(r) : "v"(lo), "v"(hi)); return r; }
; __device__ __forceinline__ float bf_lo(unsigned w) { return __uint_as_float(w << 16); }
; __device__ __forceinline__ float bf_hi(unsigned w) { return __uint_as_float(w & 0xffff0000u); }
; __device__ __forceinline__ float shx(float v, int lane, int mask) { return __int_as_float(__builtin_amdgcn_ds_bpermute((lane ^ mask) << 2, __float_as_int(v))); }
; __device__ __forceinline__ float x32_sum(float v) { auto rr = __builtin_amdgcn_permlane32_swap(__float_as_uint(v), __float_as_uint(v), false, false); return __uint_as_float(rr[0]) + __uint_as_float(rr[1]); }
;     __device__ __forceinline__ void operator()(const f32x4 (&acc)[2][2][4][2], const Unit& u, int wr, int wc, int fr, int fq, const PG8_LAS float* tab) const {
;     ...
;                     if (mode == 0) { a0 = *(const GAS f32x4*)(xo + col0); a1 = *(const GAS f32x4*)(xo + col0 + 4); }
;                     else { const u32x4 w = *(const GAS u32x4*)(xr + col0);
;                         a0 = (f32x4){bf_lo(w.x), bf_hi(w.x), bf_lo(w.y), bf_hi(w.y)}; a1 = (f32x4){bf_lo(w.z), bf_hi(w.z), bf_lo(w.w), bf_hi(w.w)}; }
;                     const f32x4 v0 = a0 + acc[ai][bj][m][0] * ra, v1 = a1 + acc[ai][bj][m][1] * ra;
;                     ssq += (v0[0] * v0[0] + v0[1] * v0[1]) + (v0[2] * v0[2] + v0[3] * v0[3]) + (v1[0] * v1[0] + v1[1] * v1[1]) + (v1[2] * v1[2] + v1[3] * v1[3]);
;                     u32x4 w; w.x = cvt_pk_bf16(v0[0], v0[1]); w.y = cvt_pk_bf16(v0[2], v0[3]); w.z = cvt_pk_bf16(v1[0], v1[1]); w.w = cvt_pk_bf16(v1[2], v1[3]);
;                     *(GAS u32x4*)(xr + col0) = w;
;                 }
;                 { const int ln = fr + 16 * fq; ssq += shx(ssq, ln, 16); ssq = x32_sum(ssq); }
;                 if (fq == 0) unsafeAtomicAdd(SSn + row, ssq);
	v_add_f32_e32 v166, v166, v167
	v_mov_b32_e32 v167, v166
	s_nop 1
	v_permlane32_swap_b32_e32 v166, v167
	s_and_saveexec_b64 s[6:7], s[8:9]
	v_add_f32_e32 v166, v166, v167
	v_lshlrev_b32_e32 v167, 2, v1
	global_atomic_add_f32 v167, v166, s[26:27] offset:512
	s_mov_b64 exec, s[6:7]
	ds_bpermute_b32 v169, v172, v168
	v_pk_mul_f32 v[30:31], v[30:31], v[134:135] op_sel_hi:[1,0]
	v_pk_mul_f32 v[32:33], v[32:33], v[134:135] op_sel_hi:[1,0]
	v_pk_mul_f32 v[26:27], v[26:27], v[134:135] op_sel_hi:[1,0]
	v_pk_mul_f32 v[28:29], v[28:29], v[134:135] op_sel_hi:[1,0]
	v_cvt_pk_bf16_f32 v158, v30, v31
	v_cvt_pk_bf16_f32 v159, v32, v33
	v_cvt_pk_bf16_f32 v160, v26, v27
	v_cvt_pk_bf16_f32 v161, v28, v29
	s_add_u32 s72, s24, 0xa0000
	s_addc_u32 s73, s25, 0
	global_store_dwordx4 v146, v[158:161], s[72:73] offset:0
	v_mul_f32_e32 v175, v31, v31
	v_mul_f32_e32 v253, v33, v33
	v_fmac_f32_e32 v175, v30, v30
	v_fmac_f32_e32 v253, v32, v32
	v_add_f32_e32 v147, v175, v253
	v_mul_f32_e32 v253, v27, v27
	v_fmac_f32_e32 v253, v26, v26
	v_mul_f32_e32 v175, v29, v29
	v_add_f32_e32 v147, v253, v147
	v_fmac_f32_e32 v175, v28, v28
	v_add_f32_e32 v147, v175, v147
	v_pk_mul_f32 v[22:23], v[22:23], v[134:135] op_sel_hi:[1,0]
	v_pk_mul_f32 v[24:25], v[24:25], v[134:135] op_sel_hi:[1,0]
	v_pk_mul_f32 v[18:19], v[18:19], v[134:135] op_sel_hi:[1,0]
	v_pk_mul_f32 v[20:21], v[20:21], v[134:135] op_sel_hi:[1,0]
	v_cvt_pk_bf16_f32 v162, v22, v23
	v_cvt_pk_bf16_f32 v163, v24, v25
	v_cvt_pk_bf16_f32 v164, v18, v19
	v_cvt_pk_bf16_f32 v165, v20, v21
	global_store_dwordx4 v146, v[162:165], s[72:73] offset:256
	v_mul_f32_e32 v175, v23, v23
	v_mul_f32_e32 v253, v25, v25
	v_fmac_f32_e32 v175, v22, v22
	v_fmac_f32_e32 v253, v24, v24
	v_add_f32_e32 v166, v175, v253
	v_mul_f32_e32 v253, v19, v19
	v_fmac_f32_e32 v253, v18, v18
	v_mul_f32_e32 v175, v21, v21
	v_add_f32_e32 v166, v253, v166
	v_fmac_f32_e32 v175, v20, v20
	v_add_f32_e32 v166, v175, v166
	v_add_f32_e32 v166, v147, v166
	s_waitcnt lgkmcnt(0)
	v_add_f32_e32 v168, v168, v169
	v_mov_b32_e32 v169, v168
	s_nop 1
	v_permlane32_swap_b32_e32 v168, v169
	s_and_saveexec_b64 s[6:7], s[8:9]
	v_add_f32_e32 v168, v168, v169
	v_lshlrev_b32_e32 v169, 2, v1
	global_atomic_add_f32 v169, v168, s[26:27] offset:576
	s_mov_b64 exec, s[6:7]
	ds_bpermute_b32 v167, v172, v166
	v_pk_mul_f32 v[14:15], v[14:15], v[136:137] op_sel_hi:[1,0]
	v_pk_mul_f32 v[16:17], v[16:17], v[136:137] op_sel_hi:[1,0]
	v_pk_mul_f32 v[10:11], v[10:11], v[136:137] op_sel_hi:[1,0]
	v_pk_mul_f32 v[12:13], v[12:13], v[136:137] op_sel_hi:[1,0]
	v_cvt_pk_bf16_f32 v158, v14, v15
	v_cvt_pk_bf16_f32 v159, v16, v17
	v_cvt_pk_bf16_f32 v160, v10, v11
	v_cvt_pk_bf16_f32 v161, v12, v13
	s_add_u32 s72, s24, 0xb0000
	s_addc_u32 s73, s25, 0
	global_store_dwordx4 v146, v[158:161], s[72:73] offset:0
	v_mul_f32_e32 v175, v15, v15
	v_mul_f32_e32 v253, v17, v17
	v_fmac_f32_e32 v175, v14, v14
	v_fmac_f32_e32 v253, v16, v16
	v_add_f32_e32 v147, v175, v253
	v_mul_f32_e32 v253, v11, v11
	v_fmac_f32_e32 v253, v10, v10
	v_mul_f32_e32 v175, v13, v13
	v_add_f32_e32 v147, v253, v147
	v_fmac_f32_e32 v175, v12, v12
	v_add_f32_e32 v147, v175, v147
	s_waitcnt vmcnt(29)
	s_cmp_eq_u32 s92, 0
	s_cbranch_scc1 .Lrf_epi_f32
	v_lshlrev_b32_e32 v240, 16, v228
	v_and_b32_e32 v241, 0xffff0000, v228
	v_lshlrev_b32_e32 v242, 16, v229
	v_and_b32_e32 v243, 0xffff0000, v229
	v_lshlrev_b32_e32 v244, 16, v230
	v_and_b32_e32 v245, 0xffff0000, v230
	v_lshlrev_b32_e32 v246, 16, v231
	v_and_b32_e32 v247, 0xffff0000, v231
.Lrf_epi_f32:
	v_fmac_f32_e32 v6, v240, v248
	v_fmac_f32_e32 v7, v241, v248
	v_fmac_f32_e32 v8, v242, v248
	v_fmac_f32_e32 v9, v243, v248
	v_fmac_f32_e32 v2, v244, v248
	v_fmac_f32_e32 v3, v245, v248
	v_fmac_f32_e32 v4, v246, v248
	v_fmac_f32_e32 v5, v247, v248
	v_pk_mul_f32 v[6:7], v[6:7], v[136:137] op_sel_hi:[1,0]
	v_pk_mul_f32 v[8:9], v[8:9], v[136:137] op_sel_hi:[1,0]
	v_pk_mul_f32 v[2:3], v[2:3], v[136:137] op_sel_hi:[1,0]
	v_pk_mul_f32 v[4:5], v[4:5], v[136:137] op_sel_hi:[1,0]
	v_cvt_pk_bf16_f32 v162, v6, v7
	v_cvt_pk_bf16_f32 v163, v8, v9
	v_cvt_pk_bf16_f32 v164, v2, v3
	v_cvt_pk_bf16_f32 v165, v4, v5
	global_store_dwordx4 v146, v[162:165], s[72:73] offset:256
	v_mul_f32_e32 v175, v7, v7
	v_mul_f32_e32 v253, v9, v9
	v_fmac_f32_e32 v175, v6, v6
	v_fmac_f32_e32 v253, v8, v8
	v_add_f32_e32 v168, v175, v253
	v_mul_f32_e32 v253, v3, v3
	v_fmac_f32_e32 v253, v2, v2
	v_mul_f32_e32 v175, v5, v5
	v_add_f32_e32 v168, v253, v168
	v_fmac_f32_e32 v175, v4, v4
	v_add_f32_e32 v168, v175, v168
	v_add_f32_e32 v168, v147, v168
	s_waitcnt lgkmcnt(0)
	v_add_f32_e32 v166, v166, v167
	v_mov_b32_e32 v167, v166
	s_nop 1
	v_permlane32_swap_b32_e32 v166, v167
	s_and_saveexec_b64 s[6:7], s[8:9]
	v_add_f32_e32 v166, v166, v167
	v_lshlrev_b32_e32 v167, 2, v1
	global_atomic_add_f32 v167, v166, s[26:27] offset:640
	s_mov_b64 exec, s[6:7]
	ds_bpermute_b32 v169, v172, v168
	s_waitcnt lgkmcnt(0)
	v_add_f32_e32 v168, v168, v169
	v_mov_b32_e32 v169, v168
	s_nop 1
	v_permlane32_swap_b32_e32 v168, v169
	s_and_saveexec_b64 s[6:7], s[8:9]
	v_add_f32_e32 v168, v168, v169
	v_lshlrev_b32_e32 v169, 2, v1
	global_atomic_add_f32 v169, v168, s[26:27] offset:704
	s_mov_b64 exec, s[6:7]
	s_and_b64 vcc, exec, s[4:5]
	s_mov_b64 s[4:5], -1
	s_cbranch_vccnz .LBB0_596
	s_andn2_b64 vcc, exec, s[10:11]
	s_cbranch_vccnz .LBB0_595
	s_barrier
	s_branch .LBB0_595
